# out-proj K-loop: two extra LDS-DMA per wave per K-iter stream the residual tile (x_in or X) toward cache ahead of the epilogue; all four waits vmcnt 8->9
# speedup vs baseline: 1.0099x; 1.0060x over previous
; #define PG8_STAGE(bufoff, gbase, voff) do { _Pragma("unroll") for (int _i = 0; _i < 2; ++_i) \
;         __builtin_amdgcn_global_load_lds((const unsigned*)((const char*)(gbase) + (voff)[_i]), (LAS unsigned*)(lds + (bufoff) + ldsw + _i * 8192), 16, 0, 0); } while (0)
; #define PG8_LDA(dst, b, h) do { _Pragma("unroll") for (int m = 0; m < 4; ++m) _Pragma("unroll") for (int k = 0; k < 2; ++k) dst[m][k] = *(const LAS bf16x8*)(lds + PG8_SA(b, h) + aoff + m * 2048 + k * 1024); } while (0)
; #define PG8_LDB(dst, b, h) do { _Pragma("unroll") for (int n = 0; n < 2; ++n) _Pragma("unroll") for (int k = 0; k < 2; ++k) dst[n][k] = *(const LAS bf16x8*)(lds + PG8_SB(b, h) + boff + n * 2048 + k * 1024); } while (0)
; #define PG8_MMA(ai, bj, At, Bt) do { __builtin_amdgcn_s_setprio(1); _Pragma("unroll") for (int m = 0; m < 4; ++m) _Pragma("unroll") for (int n = 0; n < 2; ++n) _Pragma("unroll") for (int k = 0; k < 2; ++k) \
;         acc[ai][bj][m][n] = __builtin_amdgcn_mfma_f32_16x16x32_bf16(Bt[n][k], At[m][k], acc[ai][bj][m][n], 0, 0, 0); __builtin_amdgcn_s_setprio(0); } while (0)
; #define PG8_WAIT_V(n) asm volatile("s_waitcnt vmcnt(" #n ")" ::: "memory")
; #define PG8_WAIT_L(n) asm volatile("s_waitcnt lgkmcnt(" #n ")" ::: "memory")
; #define PG8_BAR __builtin_amdgcn_s_barrier()
; #define PG8_SCHED __builtin_amdgcn_sched_barrier(0)
; template <class Epi, bool ALIGN_EPI>
; __device__ __forceinline__ void gemm_phase(LAS unsigned char* lds, const Gemm g, int G, int cid, const Epi& E) {
;     ...
;             PG8_LDB(B0, 0, 0); PG8_LDB(B1, 0, 1); PG8_SCHED; PG8_LDA(At, 0, 0); PG8_STAGE(PG8_SA(1, 1), a1 + hA, voffA);
;             PG8_WAIT_V(8); PG8_WAIT_L(0); PG8_BAR; PG8_MMA(0, 0, At, B0); PG8_MMA(0, 1, At, B1); PG8_BAR; PG8_SCHED;
;     ...
;         for (int a = 0; a < 2; ++a)
; #pragma unroll
;             for (int b = 0; b < 2; ++b)
; #pragma unroll
;                 for (int m = 0; m < 4; ++m)
; #pragma unroll
;                     for (int n = 0; n < 2; ++n) acc[a][b][m][n] = (f32x4){0.f, 0.f, 0.f, 0.f};
;         cur = nxt; cA = nA; cB = nB; ++ui;
.LBB0_726:
	s_and_b32 s30, s72, 0x7fffffff
	s_lshl_b64 s[44:45], s[30:31], 14
	s_add_u32 s44, s1, s44
	s_addc_u32 s45, s24, s45
	s_and_b64 s[42:43], s[42:43], exec
	s_cselect_b32 s30, s45, s49
	s_cselect_b32 s74, s44, s48
	s_add_u32 s75, s48, 0x80000
	v_mov_b32_e32 v0, 0
	s_addc_u32 s76, s49, 0
	s_mov_b32 s77, -2
	s_waitcnt lgkmcnt(0)
	v_mov_b32_e32 v1, v0
	v_mov_b32_e32 v2, v0
	v_mov_b32_e32 v3, v0
	v_mov_b32_e32 v4, v0
	v_mov_b32_e32 v5, v0
	v_mov_b32_e32 v6, v0
	v_mov_b32_e32 v7, v0
	v_mov_b32_e32 v16, v0
	v_mov_b32_e32 v17, v0
	v_mov_b32_e32 v18, v0
	v_mov_b32_e32 v19, v0
	v_mov_b32_e32 v20, v0
	v_mov_b32_e32 v21, v0
	v_mov_b32_e32 v22, v0
	v_mov_b32_e32 v23, v0
	v_mov_b32_e32 v32, v0
	v_mov_b32_e32 v33, v0
	v_mov_b32_e32 v34, v0
	v_mov_b32_e32 v35, v0
	v_mov_b32_e32 v36, v0
	v_mov_b32_e32 v37, v0
	v_mov_b32_e32 v38, v0
	v_mov_b32_e32 v39, v0
	v_mov_b32_e32 v48, v0
	v_mov_b32_e32 v49, v0
	v_mov_b32_e32 v50, v0
	v_mov_b32_e32 v51, v0
	v_mov_b32_e32 v52, v0
	v_mov_b32_e32 v53, v0
	v_mov_b32_e32 v54, v0
	v_mov_b32_e32 v55, v0
	v_mov_b32_e32 v8, v0
	v_mov_b32_e32 v9, v0
	v_mov_b32_e32 v10, v0
	v_mov_b32_e32 v11, v0
	v_mov_b32_e32 v12, v0
	v_mov_b32_e32 v13, v0
	v_mov_b32_e32 v14, v0
	v_mov_b32_e32 v15, v0
	v_mov_b32_e32 v24, v0
	v_mov_b32_e32 v25, v0
	v_mov_b32_e32 v26, v0
	v_mov_b32_e32 v27, v0
	v_mov_b32_e32 v28, v0
	v_mov_b32_e32 v29, v0
	v_mov_b32_e32 v30, v0
	v_mov_b32_e32 v31, v0
	v_mov_b32_e32 v40, v0
	v_mov_b32_e32 v41, v0
	v_mov_b32_e32 v42, v0
	v_mov_b32_e32 v43, v0
	v_mov_b32_e32 v44, v0
	v_mov_b32_e32 v45, v0
	v_mov_b32_e32 v46, v0
	v_mov_b32_e32 v47, v0
	v_mov_b32_e32 v56, v0
	v_mov_b32_e32 v57, v0
	v_mov_b32_e32 v58, v0
	v_mov_b32_e32 v59, v0
	v_mov_b32_e32 v60, v0
	v_mov_b32_e32 v61, v0
	v_mov_b32_e32 v62, v0
	v_mov_b32_e32 v63, v0
	v_mov_b32_e32 v64, v0
	v_mov_b32_e32 v65, v0
	v_mov_b32_e32 v66, v0
	v_mov_b32_e32 v67, v0
	v_mov_b32_e32 v68, v0
	v_mov_b32_e32 v69, v0
	v_mov_b32_e32 v70, v0
	v_mov_b32_e32 v71, v0
	v_mov_b32_e32 v80, v0
	v_mov_b32_e32 v81, v0
	v_mov_b32_e32 v82, v0
	v_mov_b32_e32 v83, v0
	v_mov_b32_e32 v84, v0
	v_mov_b32_e32 v85, v0
	v_mov_b32_e32 v86, v0
	v_mov_b32_e32 v87, v0
	v_mov_b32_e32 v96, v0
	v_mov_b32_e32 v97, v0
	v_mov_b32_e32 v98, v0
	v_mov_b32_e32 v99, v0
	v_mov_b32_e32 v100, v0
	v_mov_b32_e32 v101, v0
	v_mov_b32_e32 v102, v0
	v_mov_b32_e32 v103, v0
	v_mov_b32_e32 v120, v0
	v_mov_b32_e32 v121, v0
	v_mov_b32_e32 v122, v0
	v_mov_b32_e32 v123, v0
	v_mov_b32_e32 v124, v0
	v_mov_b32_e32 v125, v0
	v_mov_b32_e32 v126, v0
	v_mov_b32_e32 v127, v0
	v_mov_b32_e32 v72, v0
	v_mov_b32_e32 v73, v0
	v_mov_b32_e32 v74, v0
	v_mov_b32_e32 v75, v0
	v_mov_b32_e32 v76, v0
	v_mov_b32_e32 v77, v0
	v_mov_b32_e32 v78, v0
	v_mov_b32_e32 v79, v0
	v_mov_b32_e32 v88, v0
	v_mov_b32_e32 v89, v0
	v_mov_b32_e32 v90, v0
	v_mov_b32_e32 v91, v0
	v_mov_b32_e32 v92, v0
	v_mov_b32_e32 v93, v0
	v_mov_b32_e32 v94, v0
	v_mov_b32_e32 v95, v0
	v_mov_b32_e32 v104, v0
	v_mov_b32_e32 v105, v0
	v_mov_b32_e32 v106, v0
	v_mov_b32_e32 v107, v0
	v_mov_b32_e32 v108, v0
	v_mov_b32_e32 v109, v0
	v_mov_b32_e32 v110, v0
	v_mov_b32_e32 v111, v0
	s_waitcnt vmcnt(0)
	v_mov_b32_e32 v148, v0
	v_mov_b32_e32 v149, v0
	v_mov_b32_e32 v150, v0
	v_mov_b32_e32 v151, v0
	v_mov_b32_e32 v152, v0
	v_mov_b32_e32 v153, v0
	v_mov_b32_e32 v154, v0
	v_mov_b32_e32 v155, v0
	v_mbcnt_lo_u32_b32 v224, -1, 0
	v_mbcnt_hi_u32_b32 v224, -1, v224
	v_lshlrev_b32_e32 v224, 4, v224
.LBB0_727:
	s_add_u32 s42, s46, 0x100
	s_addc_u32 s43, s47, 0
	s_add_i32 s6, 0, 0x10000
	s_cmp_eq_u32 s77, 28
	s_cselect_b32 s51, s29, s43
	s_cselect_b32 s50, s28, s42
	s_cselect_b32 s49, s30, s76
	s_cselect_b32 s48, s74, s75
	s_add_i32 s7, 0, 0x14000
	v_add_u32_e32 v132, s6, v220
	v_add_u32_e32 v160, s7, v220
	ds_read_b128 v[112:115], v132
	ds_read_b128 v[116:119], v132 offset:1024
	ds_read_b128 v[128:131], v132 offset:2048
	ds_read_b128 v[132:135], v132 offset:3072
	ds_read_b128 v[140:143], v160
	ds_read_b128 v[144:147], v160 offset:1024
	ds_read_b128 v[156:159], v160 offset:2048
	ds_read_b128 v[160:163], v160 offset:3072
	v_lshl_add_u64 v[198:199], s[46:47], 0, v[184:185]
	s_add_i32 m0, s52, 0xc000
	ds_read_b128 v[164:167], v222
	ds_read_b128 v[168:171], v222 offset:1024
	ds_read_b128 v[172:175], v222 offset:2048
	ds_read_b128 v[176:179], v222 offset:3072
	ds_read_b128 v[188:191], v222 offset:4096
	ds_read_b128 v[206:209], v222 offset:5120
	ds_read_b128 v[210:213], v222 offset:6144
	ds_read_b128 v[214:217], v222 offset:7168
	global_load_lds_dwordx4 v[198:199], off
	v_lshl_add_u64 v[198:199], s[46:47], 0, v[186:187]
	s_add_i32 m0, s52, 0xe000
	s_nop 0
	global_load_lds_dwordx4 v[198:199], off
	s_add_i32 vcc_lo, s77, 2
	s_lshl_b32 vcc_lo, vcc_lo, 16
	s_lshl_b32 vcc_hi, s13, 21
	s_add_i32 vcc_lo, vcc_lo, vcc_hi
	s_lshl_b32 vcc_hi, s25, 4
	s_add_i32 vcc_lo, vcc_lo, vcc_hi
	s_lshl_b32 vcc_hi, s12, 10
	s_add_i32 vcc_lo, vcc_lo, vcc_hi
	s_add_u32 vcc_lo, s22, vcc_lo
	s_addc_u32 vcc_hi, s23, 0
	s_mov_b32 m0, 0x22c00
	s_nop 0
	global_load_lds_dwordx4 v224, vcc
	s_waitcnt vmcnt(9)
	s_waitcnt lgkmcnt(0)
	s_barrier
; #define PG8_STAGE(bufoff, gbase, voff) do { _Pragma("unroll") for (int _i = 0; _i < 2; ++_i) \
;         __builtin_amdgcn_global_load_lds((const unsigned*)((const char*)(gbase) + (voff)[_i]), (LAS unsigned*)(lds + (bufoff) + ldsw + _i * 8192), 16, 0, 0); } while (0)
; #define PG8_LDA(dst, b, h) do { _Pragma("unroll") for (int m = 0; m < 4; ++m) _Pragma("unroll") for (int k = 0; k < 2; ++k) dst[m][k] = *(const LAS bf16x8*)(lds + PG8_SA(b, h) + aoff + m * 2048 + k * 1024); } while (0)
; #define PG8_MMA(ai, bj, At, Bt) do { __builtin_amdgcn_s_setprio(1); _Pragma("unroll") for (int m = 0; m < 4; ++m) _Pragma("unroll") for (int n = 0; n < 2; ++n) _Pragma("unroll") for (int k = 0; k < 2; ++k) \
;         acc[ai][bj][m][n] = __builtin_amdgcn_mfma_f32_16x16x32_bf16(Bt[n][k], At[m][k], acc[ai][bj][m][n], 0, 0, 0); __builtin_amdgcn_s_setprio(0); } while (0)
; #define PG8_WAIT_V(n) asm volatile("s_waitcnt vmcnt(" #n ")" ::: "memory")
; #define PG8_WAIT_L(n) asm volatile("s_waitcnt lgkmcnt(" #n ")" ::: "memory")
; #define PG8_BAR __builtin_amdgcn_s_barrier()
; #define PG8_SCHED __builtin_amdgcn_sched_barrier(0)
; template <class Epi, bool ALIGN_EPI>
; __device__ __forceinline__ void gemm_phase(LAS unsigned char* lds, const Gemm g, int G, int cid, const Epi& E) {
;     ...
;             PG8_WAIT_V(8); PG8_WAIT_L(0); PG8_BAR; PG8_MMA(0, 0, At, B0); PG8_MMA(0, 1, At, B1); PG8_BAR; PG8_SCHED;
;             PG8_LDA(At, 0, 1); PG8_STAGE(PG8_SB(0, 0), b2, voffB); PG8_STAGE(PG8_SB(0, 1), b2 + hB, voffB); PG8_STAGE(PG8_SA(0, 0), a2, voffA);
;             PG8_WAIT_V(8); PG8_WAIT_L(0); PG8_BAR; PG8_MMA(1, 0, At, B0); PG8_MMA(1, 1, At, B1); PG8_BAR; PG8_SCHED;
	s_setprio 1
	s_waitcnt lgkmcnt(0)
	v_mfma_f32_16x16x32_bf16 v[152:155], v[112:115], v[164:167], v[152:155]
	v_mfma_f32_16x16x32_bf16 v[148:151], v[128:131], v[164:167], v[148:151]
	v_mfma_f32_16x16x32_bf16 v[108:111], v[112:115], v[172:175], v[108:111]
	v_mfma_f32_16x16x32_bf16 v[104:107], v[128:131], v[172:175], v[104:107]
	v_mfma_f32_16x16x32_bf16 v[92:95], v[112:115], v[188:191], v[92:95]
	v_mfma_f32_16x16x32_bf16 v[88:91], v[128:131], v[188:191], v[88:91]
	v_mfma_f32_16x16x32_bf16 v[76:79], v[112:115], v[210:213], v[76:79]
	v_mfma_f32_16x16x32_bf16 v[72:75], v[128:131], v[210:213], v[72:75]
	v_mfma_f32_16x16x32_bf16 v[152:155], v[116:119], v[168:171], v[152:155]
	v_mfma_f32_16x16x32_bf16 v[148:151], v[132:135], v[168:171], v[148:151]
	v_mfma_f32_16x16x32_bf16 v[108:111], v[116:119], v[176:179], v[108:111]
	v_mfma_f32_16x16x32_bf16 v[104:107], v[132:135], v[176:179], v[104:107]
	v_mfma_f32_16x16x32_bf16 v[92:95], v[116:119], v[206:209], v[92:95]
	v_mfma_f32_16x16x32_bf16 v[88:91], v[132:135], v[206:209], v[88:91]
	v_mfma_f32_16x16x32_bf16 v[76:79], v[116:119], v[214:217], v[76:79]
	v_mfma_f32_16x16x32_bf16 v[72:75], v[132:135], v[214:217], v[72:75]
	s_setprio 0
	s_setprio 1
	v_mfma_f32_16x16x32_bf16 v[124:127], v[140:143], v[164:167], v[124:127]
	v_mfma_f32_16x16x32_bf16 v[120:123], v[156:159], v[164:167], v[120:123]
	v_mfma_f32_16x16x32_bf16 v[100:103], v[140:143], v[172:175], v[100:103]
	v_mfma_f32_16x16x32_bf16 v[96:99], v[156:159], v[172:175], v[96:99]
	v_mfma_f32_16x16x32_bf16 v[84:87], v[140:143], v[188:191], v[84:87]
	v_mfma_f32_16x16x32_bf16 v[80:83], v[156:159], v[188:191], v[80:83]
	v_mfma_f32_16x16x32_bf16 v[68:71], v[140:143], v[210:213], v[68:71]
	v_mfma_f32_16x16x32_bf16 v[64:67], v[156:159], v[210:213], v[64:67]
	v_mfma_f32_16x16x32_bf16 v[124:127], v[144:147], v[168:171], v[124:127]
	v_mfma_f32_16x16x32_bf16 v[120:123], v[160:163], v[168:171], v[120:123]
	v_mfma_f32_16x16x32_bf16 v[100:103], v[144:147], v[176:179], v[100:103]
	v_mfma_f32_16x16x32_bf16 v[96:99], v[160:163], v[176:179], v[96:99]
	v_mfma_f32_16x16x32_bf16 v[84:87], v[144:147], v[206:209], v[84:87]
	v_mfma_f32_16x16x32_bf16 v[80:83], v[160:163], v[206:209], v[80:83]
	v_mfma_f32_16x16x32_bf16 v[68:71], v[144:147], v[214:217], v[68:71]
	v_mfma_f32_16x16x32_bf16 v[64:67], v[160:163], v[214:217], v[64:67]
	s_setprio 0
	s_barrier
	s_add_i32 s6, s6, s25
	v_lshl_add_u64 v[198:199], s[48:49], 0, v[138:139]
	s_mov_b32 m0, s6
	ds_read_b128 v[164:167], v222 offset:16384
	ds_read_b128 v[168:171], v222 offset:17408
	ds_read_b128 v[172:175], v222 offset:18432
	ds_read_b128 v[176:179], v222 offset:19456
	ds_read_b128 v[188:191], v222 offset:20480
	ds_read_b128 v[206:209], v222 offset:21504
	ds_read_b128 v[210:213], v222 offset:22528
	ds_read_b128 v[214:217], v222 offset:23552
	global_load_lds_dwordx4 v[198:199], off
	s_add_i32 m0, s6, 0x2000
	s_add_u32 s46, s48, 0x2000
	v_lshl_add_u64 v[198:199], s[48:49], 0, v[136:137]
	s_addc_u32 s47, s49, 0
	s_add_i32 s6, s7, s25
	global_load_lds_dwordx4 v[198:199], off
	v_lshl_add_u64 v[198:199], s[46:47], 0, v[138:139]
	s_mov_b32 m0, s6
	v_lshl_add_u64 v[200:201], s[50:51], 0, v[180:181]
	global_load_lds_dwordx4 v[198:199], off
	v_lshl_add_u64 v[198:199], s[46:47], 0, v[136:137]
	s_add_i32 m0, s6, 0x2000
	s_nop 0
	global_load_lds_dwordx4 v[198:199], off
	v_lshl_add_u64 v[198:199], s[50:51], 0, v[182:183]
	s_mov_b32 m0, s52
	s_nop 0
	global_load_lds_dwordx4 v[198:199], off
	s_mov_b32 m0, s53
	s_nop 0
	global_load_lds_dwordx4 v[200:201], off
	s_waitcnt vmcnt(9)
	s_waitcnt lgkmcnt(0)
	s_barrier
	s_setprio 1
	s_waitcnt lgkmcnt(0)
	v_mfma_f32_16x16x32_bf16 v[60:63], v[112:115], v[164:167], v[60:63]
	v_mfma_f32_16x16x32_bf16 v[56:59], v[128:131], v[164:167], v[56:59]
	v_mfma_f32_16x16x32_bf16 v[44:47], v[112:115], v[172:175], v[44:47]
	v_mfma_f32_16x16x32_bf16 v[40:43], v[128:131], v[172:175], v[40:43]
	v_mfma_f32_16x16x32_bf16 v[28:31], v[112:115], v[188:191], v[28:31]
	v_mfma_f32_16x16x32_bf16 v[24:27], v[128:131], v[188:191], v[24:27]
	v_mfma_f32_16x16x32_bf16 v[12:15], v[112:115], v[210:213], v[12:15]
	v_mfma_f32_16x16x32_bf16 v[8:11], v[128:131], v[210:213], v[8:11]
	v_mfma_f32_16x16x32_bf16 v[60:63], v[116:119], v[168:171], v[60:63]
	v_mfma_f32_16x16x32_bf16 v[56:59], v[132:135], v[168:171], v[56:59]
	v_mfma_f32_16x16x32_bf16 v[44:47], v[116:119], v[176:179], v[44:47]
	v_mfma_f32_16x16x32_bf16 v[40:43], v[132:135], v[176:179], v[40:43]
	v_mfma_f32_16x16x32_bf16 v[28:31], v[116:119], v[206:209], v[28:31]
	v_mfma_f32_16x16x32_bf16 v[24:27], v[132:135], v[206:209], v[24:27]
	v_mfma_f32_16x16x32_bf16 v[12:15], v[116:119], v[214:217], v[12:15]
	v_mfma_f32_16x16x32_bf16 v[8:11], v[132:135], v[214:217], v[8:11]
	s_setprio 0
	s_setprio 1
	v_mfma_f32_16x16x32_bf16 v[52:55], v[140:143], v[164:167], v[52:55]
	v_mfma_f32_16x16x32_bf16 v[48:51], v[156:159], v[164:167], v[48:51]
	v_mfma_f32_16x16x32_bf16 v[36:39], v[140:143], v[172:175], v[36:39]
	v_mfma_f32_16x16x32_bf16 v[32:35], v[156:159], v[172:175], v[32:35]
	v_mfma_f32_16x16x32_bf16 v[20:23], v[140:143], v[188:191], v[20:23]
	v_mfma_f32_16x16x32_bf16 v[16:19], v[156:159], v[188:191], v[16:19]
	v_mfma_f32_16x16x32_bf16 v[4:7], v[140:143], v[210:213], v[4:7]
	v_mfma_f32_16x16x32_bf16 v[0:3], v[156:159], v[210:213], v[0:3]
	v_mfma_f32_16x16x32_bf16 v[52:55], v[144:147], v[168:171], v[52:55]
	v_mfma_f32_16x16x32_bf16 v[48:51], v[160:163], v[168:171], v[48:51]
	v_mfma_f32_16x16x32_bf16 v[36:39], v[144:147], v[176:179], v[36:39]
	v_mfma_f32_16x16x32_bf16 v[32:35], v[160:163], v[176:179], v[32:35]
	v_mfma_f32_16x16x32_bf16 v[20:23], v[144:147], v[206:209], v[20:23]
	v_mfma_f32_16x16x32_bf16 v[16:19], v[160:163], v[206:209], v[16:19]
	v_mfma_f32_16x16x32_bf16 v[4:7], v[144:147], v[214:217], v[4:7]
	v_mfma_f32_16x16x32_bf16 v[0:3], v[160:163], v[214:217], v[0:3]
	s_setprio 0
	s_barrier
; #define PG8_STAGE(bufoff, gbase, voff) do { _Pragma("unroll") for (int _i = 0; _i < 2; ++_i) \
;         __builtin_amdgcn_global_load_lds((const unsigned*)((const char*)(gbase) + (voff)[_i]), (LAS unsigned*)(lds + (bufoff) + ldsw + _i * 8192), 16, 0, 0); } while (0)
; #define PG8_LDA(dst, b, h) do { _Pragma("unroll") for (int m = 0; m < 4; ++m) _Pragma("unroll") for (int k = 0; k < 2; ++k) dst[m][k] = *(const LAS bf16x8*)(lds + PG8_SA(b, h) + aoff + m * 2048 + k * 1024); } while (0)
; #define PG8_LDB(dst, b, h) do { _Pragma("unroll") for (int n = 0; n < 2; ++n) _Pragma("unroll") for (int k = 0; k < 2; ++k) dst[n][k] = *(const LAS bf16x8*)(lds + PG8_SB(b, h) + boff + n * 2048 + k * 1024); } while (0)
; #define PG8_MMA(ai, bj, At, Bt) do { __builtin_amdgcn_s_setprio(1); _Pragma("unroll") for (int m = 0; m < 4; ++m) _Pragma("unroll") for (int n = 0; n < 2; ++n) _Pragma("unroll") for (int k = 0; k < 2; ++k) \
;         acc[ai][bj][m][n] = __builtin_amdgcn_mfma_f32_16x16x32_bf16(Bt[n][k], At[m][k], acc[ai][bj][m][n], 0, 0, 0); __builtin_amdgcn_s_setprio(0); } while (0)
; #define PG8_WAIT_V(n) asm volatile("s_waitcnt vmcnt(" #n ")" ::: "memory")
; #define PG8_WAIT_L(n) asm volatile("s_waitcnt lgkmcnt(" #n ")" ::: "memory")
; #define PG8_BAR __builtin_amdgcn_s_barrier()
; #define PG8_SCHED __builtin_amdgcn_sched_barrier(0)
; template <class Epi, bool ALIGN_EPI>
; __device__ __forceinline__ void gemm_phase(LAS unsigned char* lds, const Gemm g, int G, int cid, const Epi& E) {
;     ...
;             PG8_LDB(B0, 1, 0); PG8_LDB(B1, 1, 1); PG8_SCHED; PG8_LDA(At, 1, 0); PG8_STAGE(PG8_SA(0, 1), a2 + hA, voffA);
;             PG8_WAIT_V(8); PG8_WAIT_L(0); PG8_BAR; PG8_MMA(0, 0, At, B0); PG8_MMA(0, 1, At, B1); PG8_BAR; PG8_SCHED;
;             PG8_LDA(At, 1, 1); PG8_STAGE(PG8_SB(1, 0), b3, voffB); PG8_STAGE(PG8_SB(1, 1), b3 + hB, voffB); PG8_STAGE(PG8_SA(1, 0), a3, voffA);
;             PG8_WAIT_V(8); PG8_WAIT_L(0); PG8_BAR; PG8_MMA(1, 0, At, B0); PG8_MMA(1, 1, At, B1); PG8_BAR; PG8_SCHED;
	s_add_i32 s6, 0, 0x18000
	s_add_i32 s7, 0, 0x1c000
	v_add_u32_e32 v132, s6, v220
	v_add_u32_e32 v160, s7, v220
	ds_read_b128 v[112:115], v132
	ds_read_b128 v[116:119], v132 offset:1024
	ds_read_b128 v[128:131], v132 offset:2048
	ds_read_b128 v[132:135], v132 offset:3072
	ds_read_b128 v[140:143], v160
	ds_read_b128 v[144:147], v160 offset:1024
	ds_read_b128 v[156:159], v160 offset:2048
	ds_read_b128 v[160:163], v160 offset:3072
	s_add_u32 s46, s50, 0x84000
	s_addc_u32 s47, s51, 0
	s_mov_b32 m0, s54
	v_lshl_add_u64 v[218:219], s[46:47], 0, v[182:183]
	ds_read_b128 v[164:167], v222 offset:32768
	ds_read_b128 v[168:171], v222 offset:33792
	ds_read_b128 v[172:175], v222 offset:34816
	ds_read_b128 v[176:179], v222 offset:35840
	ds_read_b128 v[188:191], v222 offset:36864
	ds_read_b128 v[206:209], v222 offset:37888
	ds_read_b128 v[210:213], v222 offset:38912
	ds_read_b128 v[214:217], v222 offset:39936
	global_load_lds_dwordx4 v[218:219], off
	v_lshl_add_u64 v[218:219], s[46:47], 0, v[180:181]
	s_mov_b32 m0, s55
	s_nop 0
	global_load_lds_dwordx4 v[218:219], off
	s_add_u32 vcc_lo, vcc_lo, 0x2000
	s_addc_u32 vcc_hi, vcc_hi, 0
	s_mov_b32 m0, 0x22c00
	s_nop 0
	global_load_lds_dwordx4 v224, vcc
	s_waitcnt vmcnt(9)
	s_waitcnt lgkmcnt(0)
	s_barrier
	s_setprio 1
	s_waitcnt lgkmcnt(0)
	v_mfma_f32_16x16x32_bf16 v[152:155], v[112:115], v[164:167], v[152:155]
	v_mfma_f32_16x16x32_bf16 v[148:151], v[128:131], v[164:167], v[148:151]
	v_mfma_f32_16x16x32_bf16 v[108:111], v[112:115], v[172:175], v[108:111]
	v_mfma_f32_16x16x32_bf16 v[104:107], v[128:131], v[172:175], v[104:107]
	v_mfma_f32_16x16x32_bf16 v[92:95], v[112:115], v[188:191], v[92:95]
	v_mfma_f32_16x16x32_bf16 v[88:91], v[128:131], v[188:191], v[88:91]
	v_mfma_f32_16x16x32_bf16 v[76:79], v[112:115], v[210:213], v[76:79]
	v_mfma_f32_16x16x32_bf16 v[72:75], v[128:131], v[210:213], v[72:75]
	v_mfma_f32_16x16x32_bf16 v[152:155], v[116:119], v[168:171], v[152:155]
	v_mfma_f32_16x16x32_bf16 v[148:151], v[132:135], v[168:171], v[148:151]
	v_mfma_f32_16x16x32_bf16 v[108:111], v[116:119], v[176:179], v[108:111]
	v_mfma_f32_16x16x32_bf16 v[104:107], v[132:135], v[176:179], v[104:107]
	v_mfma_f32_16x16x32_bf16 v[92:95], v[116:119], v[206:209], v[92:95]
	v_mfma_f32_16x16x32_bf16 v[88:91], v[132:135], v[206:209], v[88:91]
	v_mfma_f32_16x16x32_bf16 v[76:79], v[116:119], v[214:217], v[76:79]
	v_mfma_f32_16x16x32_bf16 v[72:75], v[132:135], v[214:217], v[72:75]
	s_setprio 0
	s_setprio 1
	v_mfma_f32_16x16x32_bf16 v[124:127], v[140:143], v[164:167], v[124:127]
	v_mfma_f32_16x16x32_bf16 v[120:123], v[156:159], v[164:167], v[120:123]
	v_mfma_f32_16x16x32_bf16 v[100:103], v[140:143], v[172:175], v[100:103]
	v_mfma_f32_16x16x32_bf16 v[96:99], v[156:159], v[172:175], v[96:99]
	v_mfma_f32_16x16x32_bf16 v[84:87], v[140:143], v[188:191], v[84:87]
	v_mfma_f32_16x16x32_bf16 v[80:83], v[156:159], v[188:191], v[80:83]
	v_mfma_f32_16x16x32_bf16 v[68:71], v[140:143], v[210:213], v[68:71]
	v_mfma_f32_16x16x32_bf16 v[64:67], v[156:159], v[210:213], v[64:67]
	v_mfma_f32_16x16x32_bf16 v[124:127], v[144:147], v[168:171], v[124:127]
	v_mfma_f32_16x16x32_bf16 v[120:123], v[160:163], v[168:171], v[120:123]
	v_mfma_f32_16x16x32_bf16 v[100:103], v[144:147], v[176:179], v[100:103]
	v_mfma_f32_16x16x32_bf16 v[96:99], v[160:163], v[176:179], v[96:99]
	v_mfma_f32_16x16x32_bf16 v[84:87], v[144:147], v[206:209], v[84:87]
	v_mfma_f32_16x16x32_bf16 v[80:83], v[160:163], v[206:209], v[80:83]
	v_mfma_f32_16x16x32_bf16 v[68:71], v[144:147], v[214:217], v[68:71]
	v_mfma_f32_16x16x32_bf16 v[64:67], v[160:163], v[214:217], v[64:67]
	s_setprio 0
	s_barrier
	s_add_u32 s46, s48, 0x40000
	s_addc_u32 s47, s49, 0
	s_add_i32 s6, s6, s25
	v_lshl_add_u64 v[218:219], s[46:47], 0, v[138:139]
	s_mov_b32 m0, s6
	ds_read_b128 v[164:167], v222 offset:49152
	ds_read_b128 v[168:171], v222 offset:50176
	ds_read_b128 v[172:175], v222 offset:51200
	ds_read_b128 v[176:179], v222 offset:52224
	ds_read_b128 v[188:191], v222 offset:53248
	ds_read_b128 v[206:209], v222 offset:54272
	ds_read_b128 v[210:213], v222 offset:55296
	ds_read_b128 v[214:217], v222 offset:56320
	global_load_lds_dwordx4 v[218:219], off
	s_add_i32 m0, s6, 0x2000
	v_lshl_add_u64 v[218:219], s[46:47], 0, v[136:137]
	s_add_u32 s46, s48, 0x42000
	s_addc_u32 s47, s49, 0
	s_add_i32 s6, s7, s25
	global_load_lds_dwordx4 v[218:219], off
	v_lshl_add_u64 v[218:219], s[46:47], 0, v[138:139]
	s_mov_b32 m0, s6
	v_lshl_add_u64 v[198:199], v[198:199], 0, s[36:37]
	global_load_lds_dwordx4 v[218:219], off
	v_lshl_add_u64 v[218:219], s[46:47], 0, v[136:137]
	s_add_i32 m0, s6, 0x2000
	s_nop 0
	global_load_lds_dwordx4 v[218:219], off
	s_mov_b32 m0, s58
	s_nop 0
	global_load_lds_dwordx4 v[198:199], off
	v_lshl_add_u64 v[198:199], v[200:201], 0, s[36:37]
	s_mov_b32 m0, s59
	s_nop 0
	global_load_lds_dwordx4 v[198:199], off
	s_waitcnt vmcnt(9)
	s_waitcnt lgkmcnt(0)
	s_barrier
; #define PG8_MMA(ai, bj, At, Bt) do { __builtin_amdgcn_s_setprio(1); _Pragma("unroll") for (int m = 0; m < 4; ++m) _Pragma("unroll") for (int n = 0; n < 2; ++n) _Pragma("unroll") for (int k = 0; k < 2; ++k) \
;         acc[ai][bj][m][n] = __builtin_amdgcn_mfma_f32_16x16x32_bf16(Bt[n][k], At[m][k], acc[ai][bj][m][n], 0, 0, 0); __builtin_amdgcn_s_setprio(0); } while (0)
; #define PG8_WAIT_V(n) asm volatile("s_waitcnt vmcnt(" #n ")" ::: "memory")
; #define PG8_WAIT_L(n) asm volatile("s_waitcnt lgkmcnt(" #n ")" ::: "memory")
; #define PG8_BAR __builtin_amdgcn_s_barrier()
; #define PG8_SCHED __builtin_amdgcn_sched_barrier(0)
; template <class Epi, bool ALIGN_EPI>
; __device__ __forceinline__ void gemm_phase(LAS unsigned char* lds, const Gemm g, int G, int cid, const Epi& E) {
;     ...
;             PG8_WAIT_V(8); PG8_WAIT_L(0); PG8_BAR; PG8_MMA(1, 0, At, B0); PG8_MMA(1, 1, At, B1); PG8_BAR; PG8_SCHED;
;         }
	s_setprio 1
	s_waitcnt lgkmcnt(0)
	v_mfma_f32_16x16x32_bf16 v[60:63], v[112:115], v[164:167], v[60:63]
	v_mfma_f32_16x16x32_bf16 v[56:59], v[128:131], v[164:167], v[56:59]
	v_mfma_f32_16x16x32_bf16 v[44:47], v[112:115], v[172:175], v[44:47]
	v_mfma_f32_16x16x32_bf16 v[40:43], v[128:131], v[172:175], v[40:43]
	v_mfma_f32_16x16x32_bf16 v[28:31], v[112:115], v[188:191], v[28:31]
	v_mfma_f32_16x16x32_bf16 v[24:27], v[128:131], v[188:191], v[24:27]
	v_mfma_f32_16x16x32_bf16 v[12:15], v[112:115], v[210:213], v[12:15]
	v_mfma_f32_16x16x32_bf16 v[8:11], v[128:131], v[210:213], v[8:11]
	v_mfma_f32_16x16x32_bf16 v[60:63], v[116:119], v[168:171], v[60:63]
	v_mfma_f32_16x16x32_bf16 v[56:59], v[132:135], v[168:171], v[56:59]
	v_mfma_f32_16x16x32_bf16 v[44:47], v[116:119], v[176:179], v[44:47]
	v_mfma_f32_16x16x32_bf16 v[40:43], v[132:135], v[176:179], v[40:43]
	v_mfma_f32_16x16x32_bf16 v[28:31], v[116:119], v[206:209], v[28:31]
	v_mfma_f32_16x16x32_bf16 v[24:27], v[132:135], v[206:209], v[24:27]
	v_mfma_f32_16x16x32_bf16 v[12:15], v[116:119], v[214:217], v[12:15]
	v_mfma_f32_16x16x32_bf16 v[8:11], v[132:135], v[214:217], v[8:11]
	s_setprio 0
	s_setprio 1
	v_mfma_f32_16x16x32_bf16 v[52:55], v[140:143], v[164:167], v[52:55]
	v_mfma_f32_16x16x32_bf16 v[48:51], v[156:159], v[164:167], v[48:51]
	v_mfma_f32_16x16x32_bf16 v[36:39], v[140:143], v[172:175], v[36:39]
	v_mfma_f32_16x16x32_bf16 v[32:35], v[156:159], v[172:175], v[32:35]
	v_mfma_f32_16x16x32_bf16 v[20:23], v[140:143], v[188:191], v[20:23]
	v_mfma_f32_16x16x32_bf16 v[16:19], v[156:159], v[188:191], v[16:19]
	v_mfma_f32_16x16x32_bf16 v[4:7], v[140:143], v[210:213], v[4:7]
	v_mfma_f32_16x16x32_bf16 v[0:3], v[156:159], v[210:213], v[0:3]
	v_mfma_f32_16x16x32_bf16 v[52:55], v[144:147], v[168:171], v[52:55]
	v_mfma_f32_16x16x32_bf16 v[48:51], v[160:163], v[168:171], v[48:51]
	v_mfma_f32_16x16x32_bf16 v[36:39], v[144:147], v[176:179], v[36:39]
	v_mfma_f32_16x16x32_bf16 v[32:35], v[160:163], v[176:179], v[32:35]
	v_mfma_f32_16x16x32_bf16 v[20:23], v[144:147], v[206:209], v[20:23]
	v_mfma_f32_16x16x32_bf16 v[16:19], v[160:163], v[206:209], v[16:19]
	v_mfma_f32_16x16x32_bf16 v[4:7], v[144:147], v[214:217], v[4:7]
	v_mfma_f32_16x16x32_bf16 v[0:3], v[160:163], v[214:217], v[0:3]
	s_setprio 0
	s_barrier
	s_add_i32 s77, s77, 2
	s_add_u32 s75, s75, 0x80000
	s_addc_u32 s76, s76, 0
	s_cmp_gt_u32 s77, 29
	s_mov_b64 s[46:47], s[42:43]
	s_cbranch_scc0 .LBB0_727
; __device__ __forceinline__ unsigned cvt_pk_bf16(float lo, float hi) { unsigned r; asm volatile("v_cvt_pk_bf16_f32 %0, %1, %2" : "=v"(r) : "v"(lo), "v"(hi)); return r; }
;     __device__ __forceinline__ void operator()(const f32x4 (&acc)[2][2][4][2], const Unit& u, int wr, int wc, int fr, int fq, const LAS float*) const {
;     ...
;         for (int am = 0; am < NB; ++am) { const int ai = am / (NB / 2), m0 = (am % (NB / 2)) * MB;
;             f32x4 xo[4][2][2];
; #pragma unroll
;             for (int m = m0; m < m0 + MB; ++m) { const float* xr = Xs + (size_t)(row0 + ai * HALF + m * 16) * DM + col0;
; #pragma unroll
;                 for (int bj = 0; bj < 2; ++bj) { xo[m][bj][0] = *(const f32x4*)(xr + bj * HALF); xo[m][bj][1] = *(const f32x4*)(xr + bj * HALF + 4); } }
; #pragma unroll
;             for (int m = m0; m < m0 + MB; ++m) { const int row = row0 + ai * HALF + m * 16; float ss = 0.f;
;                 float* xr = X + (size_t)row * DM + col0; bf16_t* xb = XB + (size_t)row * ALD + col0;
; #pragma unroll
;                 for (int bj = 0; bj < 2; ++bj) { f32x4 x0 = xo[m][bj][0], x1 = xo[m][bj][1];
;                     if (HB) { x0 += (acc[ai][bj][m][0] + bv[bj][0]) * sv[bj][0]; x1 += (acc[ai][bj][m][1] + bv[bj][1]) * sv[bj][1]; } else { x0 += acc[ai][bj][m][0]; x1 += acc[ai][bj][m][1]; }
;                     *(f32x4*)(xr + bj * HALF) = x0; *(f32x4*)(xr + bj * HALF + 4) = x1;
;                     ss += (x0[0] * x0[0] + x0[1] * x0[1]) + (x0[2] * x0[2] + x0[3] * x0[3]) + (x1[0] * x1[0] + x1[1] * x1[1]) + (x1[2] * x1[2] + x1[3] * x1[3]);
;                     u32x4 w; w.x = cvt_pk_bf16(x0[0], x0[1]); w.y = cvt_pk_bf16(x0[2], x0[3]); w.z = cvt_pk_bf16(x1[0], x1[1]); w.w = cvt_pk_bf16(x1[2], x1[3]);
;                     if (feeds) *(u32x4*)(xb + bj * HALF) = w; }
;                 ss += __shfl_xor(ss, 16); ss += __shfl_xor(ss, 32);
;                 if (fq == 0 && feeds) part[(size_t)row * NPART + u.pn * 4 + wc] = ss; }
	v_lshl_or_b32 v188, s12, 8, v221
	v_lshl_add_u32 v190, s13, 8, v197
	v_ashrrev_i32_e32 v189, 31, v188
	v_lshlrev_b64 v[198:199], 2, v[188:189]
	v_ashrrev_i32_e32 v191, 31, v190
	v_lshl_add_u64 v[206:207], s[22:23], 0, v[198:199]
	v_lshlrev_b64 v[200:201], 13, v[190:191]
	v_lshl_add_u64 v[112:113], v[206:207], 0, v[200:201]
	global_load_dwordx4 v[224:227], v[112:113], off offset:16
	global_load_dwordx4 v[228:231], v[112:113], off
	global_load_dwordx4 v[232:235], v[112:113], off offset:528
	global_load_dwordx4 v[244:247], v[112:113], off offset:512
	v_or_b32_e32 v214, 16, v190
	v_ashrrev_i32_e32 v215, 31, v214
	v_or_b32_e32 v210, 32, v190
	v_or_b32_e32 v208, 48, v190
	v_lshlrev_b64 v[218:219], 13, v[214:215]
	v_ashrrev_i32_e32 v211, 31, v210
	v_ashrrev_i32_e32 v209, 31, v208
	v_lshl_add_u64 v[112:113], v[206:207], 0, v[218:219]
	v_lshlrev_b64 v[216:217], 13, v[210:211]
	v_lshlrev_b64 v[212:213], 13, v[208:209]
	global_load_dwordx4 v[172:175], v[112:113], off offset:16
	global_load_dwordx4 v[176:179], v[112:113], off
	global_load_dwordx4 v[164:167], v[112:113], off offset:528
	global_load_dwordx4 v[168:171], v[112:113], off offset:512
	v_lshl_add_u64 v[112:113], v[206:207], 0, v[216:217]
	v_lshl_add_u64 v[116:117], v[206:207], 0, v[212:213]
	global_load_dwordx4 v[156:159], v[112:113], off offset:16
	global_load_dwordx4 v[160:163], v[112:113], off
	global_load_dwordx4 v[128:131], v[112:113], off offset:528
	global_load_dwordx4 v[144:147], v[112:113], off offset:512
	global_load_dwordx4 v[132:135], v[116:117], off offset:16
	global_load_dwordx4 v[140:143], v[116:117], off
	s_nop 0
	global_load_dwordx4 v[112:115], v[116:117], off offset:528
	s_nop 0
	global_load_dwordx4 v[116:119], v[116:117], off offset:512
	v_lshl_add_u64 v[200:201], s[82:83], 0, v[200:201]
	v_lshl_add_u64 v[198:199], v[200:201], 0, v[198:199]
	v_mov_b64_e32 v[200:201], s[4:5]
	s_lshl_b32 s42, s12, 2
	v_mad_i64_i32 v[200:201], s[12:13], v190, s66, v[200:201]
	v_lshl_add_u64 v[200:201], v[188:189], 1, v[200:201]
	s_ashr_i32 s43, s42, 31
	s_waitcnt vmcnt(0)
	v_pk_add_f32 v[148:149], v[148:149], v[224:225]
	v_pk_add_f32 v[154:155], v[154:155], v[230:231]
	v_pk_add_f32 v[152:153], v[152:153], v[228:229]
	v_mul_f32_e32 v224, v155, v155
	v_mul_f32_e32 v223, v153, v153
	v_fmac_f32_e32 v223, v152, v152
	v_fmac_f32_e32 v224, v154, v154
	v_add_f32_e32 v223, v223, v224
	v_mul_f32_e32 v224, v149, v149
	v_pk_add_f32 v[126:127], v[126:127], v[246:247]
	v_pk_add_f32 v[124:125], v[124:125], v[244:245]
	v_pk_add_f32 v[150:151], v[150:151], v[226:227]
	global_store_dwordx4 v[198:199], v[152:155], off
	global_store_dwordx4 v[198:199], v[148:151], off offset:16
	v_fmac_f32_e32 v224, v148, v148
	v_cvt_pk_bf16_f32 v152, v152, v153
	v_cvt_pk_bf16_f32 v153, v154, v155
	v_cvt_pk_bf16_f32 v154, v148, v149
	v_pk_add_f32 v[120:121], v[120:121], v[232:233]
	v_mul_f32_e32 v148, v125, v125
	v_mul_f32_e32 v149, v127, v127
	v_fmac_f32_e32 v148, v124, v124
	v_fmac_f32_e32 v149, v126, v126
	v_add_f32_e32 v148, v148, v149
	v_mul_f32_e32 v149, v121, v121
	v_cvt_pk_bf16_f32 v155, v150, v151
	global_store_dwordx4 v[200:201], v[152:155], off
	v_pk_add_f32 v[122:123], v[122:123], v[234:235]
	global_store_dwordx4 v[198:199], v[124:127], off offset:512
	global_store_dwordx4 v[198:199], v[120:123], off offset:528
	v_fmac_f32_e32 v149, v120, v120
	v_cvt_pk_bf16_f32 v124, v124, v125
	v_cvt_pk_bf16_f32 v125, v126, v127
	v_cvt_pk_bf16_f32 v126, v120, v121
	v_add_f32_e32 v223, v223, v224
	v_and_b32_e32 v121, 64, v239
	v_mul_f32_e32 v224, v151, v151
	v_add_f32_e32 v148, v148, v149
	v_mul_f32_e32 v149, v123, v123
	v_xor_b32_e32 v120, 16, v239
	v_add_u32_e32 v121, 64, v121
	v_fmac_f32_e32 v224, v150, v150
	v_fmac_f32_e32 v149, v122, v122
	v_cmp_lt_i32_e32 vcc, v120, v121
	v_add_f32_e32 v223, v224, v223
	v_add_f32_e32 v148, v149, v148
	v_cndmask_b32_e32 v120, v239, v120, vcc
	v_add_f32_e32 v148, v223, v148
	v_cvt_pk_bf16_f32 v127, v122, v123
	global_store_dwordx4 v[200:201], v[124:127], off offset:256
	v_xor_b32_e32 v122, 32, v239
	v_cmp_lt_i32_e32 vcc, v122, v121
	v_lshlrev_b32_e32 v126, 2, v120
	ds_bpermute_b32 v120, v126, v148
	v_cndmask_b32_e32 v121, v239, v122, vcc
	v_lshlrev_b32_e32 v127, 2, v121
	s_waitcnt lgkmcnt(0)
	v_add_f32_e32 v120, v148, v120
	ds_bpermute_b32 v121, v127, v120
	s_and_saveexec_b64 s[46:47], s[38:39]
	s_cbranch_execz .LBB0_730
	v_lshlrev_b64 v[122:123], 7, v[190:191]
	v_lshl_add_u64 v[122:123], s[94:95], 0, v[122:123]
	v_lshl_add_u64 v[122:123], s[42:43], 2, v[122:123]
	s_lshl_b32 s30, s57, 2
	v_lshl_add_u64 v[122:123], v[122:123], 0, s[30:31]
	s_waitcnt lgkmcnt(0)
	v_add_f32_e32 v120, v120, v121
	global_store_dword v[122:123], v120, off
